# neighbourhood-attention tiles: relative-position-bias LDS reads batched, applied with v_cndmask under the precomputed masks
# baseline (speedup 1.0000x reference)
.LBB0_251:
	s_bitcmp1_b32 s98, 0
	s_cselect_b32 s36, 0x4400, 0
	v_add3_u32 v36, s36, v168, v169
	ds_read_b128 v[32:35], v36
	v_add3_u32 v70, s36, v170, v169
	ds_read_b128 v[66:69], v70
	s_waitcnt lgkmcnt(1)
	v_mfma_f32_32x32x16_bf16 v[48:63], v[32:35], v[96:99], 0
	ds_read_b128 v[32:35], v36 offset:4096
	s_waitcnt lgkmcnt(1)
	v_mfma_f32_32x32x16_bf16 v[48:63], v[66:69], v[100:103], v[48:63]
	ds_read_b128 v[66:69], v70 offset:4096
	v_add3_u32 v70, s36, v172, v169
	s_waitcnt lgkmcnt(1)
	v_mfma_f32_32x32x16_bf16 v[32:47], v[32:35], v[96:99], 0
	s_waitcnt lgkmcnt(0)
	v_mfma_f32_32x32x16_bf16 v[32:47], v[66:69], v[100:103], v[32:47]
	ds_read_b128 v[66:69], v70
	s_waitcnt lgkmcnt(0)
	v_mfma_f32_32x32x16_bf16 v[48:63], v[66:69], v[104:107], v[48:63]
	ds_read_b128 v[66:69], v70 offset:4096
	v_add3_u32 v70, s36, v174, v169
	s_waitcnt lgkmcnt(0)
	v_mfma_f32_32x32x16_bf16 v[32:47], v[66:69], v[104:107], v[32:47]
	ds_read_b128 v[66:69], v70
	s_waitcnt lgkmcnt(0)
	v_mfma_f32_32x32x16_bf16 v[48:63], v[66:69], v[108:111], v[48:63]
	ds_read_b128 v[66:69], v70 offset:4096
	s_waitcnt lgkmcnt(0)
	v_mfma_f32_32x32x16_bf16 v[32:47], v[66:69], v[108:111], v[32:47]
	s_and_saveexec_b64 s[82:83], s[0:1]
	s_xor_b64 s[82:83], exec, s[82:83]
	s_cbranch_execz .LBB0_319
	s_and_b64 s[0:1], s[44:45], vcc
	s_and_saveexec_b64 vcc, s[0:1]
	s_cbranch_execz .LBB0_318
	v_sub_u32_e32 v64, v64, v150
	s_movk_i32 s0, 0x7c
	v_mad_u64_u32 v[140:141], s[0:1], v64, s0, v[136:137]
	v_mov_b32_e32 v141, 0xf149f2ca
	v_lshl_add_u32 v140, v132, 2, v140
	ds_read_b32 v64, v140 offset:35744
	ds_read_b32 v65, v140 offset:35872
	ds_read_b32 v66, v140 offset:35748
	ds_read_b32 v67, v140 offset:35876
	ds_read_b32 v68, v140 offset:35752
	ds_read_b32 v69, v140 offset:35880
	ds_read_b32 v70, v140 offset:35756
	ds_read_b32 v71, v140 offset:35884
	ds_read_b32 v72, v140 offset:35776
	ds_read_b32 v73, v140 offset:35904
	ds_read_b32 v74, v140 offset:35780
	ds_read_b32 v75, v140 offset:35908
	ds_read_b32 v76, v140 offset:35784
	ds_read_b32 v77, v140 offset:35912
	s_waitcnt lgkmcnt(7)
	v_add_f32_e32 v64, v48, v64
	v_add_f32_e32 v65, v32, v65
	v_add_f32_e32 v66, v49, v66
	v_add_f32_e32 v67, v33, v67
	v_add_f32_e32 v68, v50, v68
	v_add_f32_e32 v69, v34, v69
	v_add_f32_e32 v70, v51, v70
	v_cndmask_b32_e64 v48, v141, v64, s[46:47]
	v_cndmask_b32_e64 v32, v141, v65, s[30:31]
	v_cndmask_b32_e64 v49, v141, v66, s[48:49]
	v_cndmask_b32_e64 v33, v141, v67, s[26:27]
	v_cndmask_b32_e64 v50, v141, v68, s[50:51]
	v_cndmask_b32_e64 v34, v141, v69, s[78:79]
	v_cndmask_b32_e64 v51, v141, v70, s[52:53]
	ds_read_b32 v78, v140 offset:35788
	ds_read_b32 v79, v140 offset:35916
	ds_read_b32 v80, v140 offset:35808
	ds_read_b32 v81, v140 offset:35936
	ds_read_b32 v82, v140 offset:35812
	ds_read_b32 v83, v140 offset:35940
	ds_read_b32 v84, v140 offset:35816
	s_waitcnt lgkmcnt(7)
	v_add_f32_e32 v71, v35, v71
	v_add_f32_e32 v72, v52, v72
	v_add_f32_e32 v73, v36, v73
	v_add_f32_e32 v74, v53, v74
	v_add_f32_e32 v75, v37, v75
	v_add_f32_e32 v76, v54, v76
	v_add_f32_e32 v77, v38, v77
	v_cndmask_b32_e64 v35, v141, v71, s[2:3]
	v_cndmask_b32_e64 v52, v141, v72, s[54:55]
	v_cndmask_b32_e64 v36, v141, v73, s[18:19]
	v_cndmask_b32_e64 v53, v141, v74, s[56:57]
	v_cndmask_b32_e64 v37, v141, v75, s[22:23]
	v_cndmask_b32_e64 v54, v141, v76, s[58:59]
	v_cndmask_b32_e64 v38, v141, v77, s[20:21]
	ds_read_b32 v85, v140 offset:35944
	ds_read_b32 v86, v140 offset:35820
	ds_read_b32 v87, v140 offset:35948
	ds_read_b32 v88, v140 offset:35840
	ds_read_b32 v89, v140 offset:35968
	ds_read_b32 v90, v140 offset:35844
	ds_read_b32 v91, v140 offset:35972
	s_waitcnt lgkmcnt(7)
	v_add_f32_e32 v78, v55, v78
	v_add_f32_e32 v79, v39, v79
	v_add_f32_e32 v80, v56, v80
	v_add_f32_e32 v81, v40, v81
	v_add_f32_e32 v82, v57, v82
	v_add_f32_e32 v83, v41, v83
	v_add_f32_e32 v84, v58, v84
	v_cndmask_b32_e64 v55, v141, v78, s[60:61]
	v_cndmask_b32_e64 v39, v141, v79, s[28:29]
	v_cndmask_b32_e64 v56, v141, v80, s[24:25]
	v_cndmask_b32_e64 v40, v141, v81, s[62:63]
	v_cndmask_b32_e64 v57, v141, v82, s[38:39]
	v_cndmask_b32_e64 v41, v141, v83, s[64:65]
	v_cndmask_b32_e64 v58, v141, v84, s[8:9]
	ds_read_b32 v92, v140 offset:35848
	ds_read_b32 v93, v140 offset:35976
	ds_read_b32 v94, v140 offset:35852
	ds_read_b32 v95, v140 offset:35980
	s_waitcnt lgkmcnt(4)
	v_add_f32_e32 v85, v42, v85
	v_add_f32_e32 v86, v59, v86
	v_add_f32_e32 v87, v43, v87
	v_add_f32_e32 v88, v60, v88
	v_add_f32_e32 v89, v44, v89
	v_add_f32_e32 v90, v61, v90
	v_add_f32_e32 v91, v45, v91
	v_cndmask_b32_e64 v42, v141, v85, s[66:67]
	v_cndmask_b32_e64 v59, v141, v86, s[10:11]
	v_cndmask_b32_e64 v43, v141, v87, s[68:69]
	v_cndmask_b32_e64 v60, v141, v88, s[84:85]
	v_cndmask_b32_e64 v44, v141, v89, s[70:71]
	v_cndmask_b32_e64 v61, v141, v90, s[86:87]
	v_cndmask_b32_e64 v45, v141, v91, s[72:73]
	s_waitcnt lgkmcnt(0)
	v_add_f32_e32 v92, v62, v92
	v_add_f32_e32 v93, v46, v93
	v_add_f32_e32 v94, v63, v94
	v_add_f32_e32 v95, v47, v95
	v_cndmask_b32_e64 v62, v141, v92, s[88:89]
	v_cndmask_b32_e64 v46, v141, v93, s[74:75]
	v_cndmask_b32_e64 v63, v141, v94, s[90:91]
	v_cndmask_b32_e64 v47, v141, v95, s[76:77]
